# in-proj rotary epilogues: packed f32 ops replaced by scalar f32 ops, dead halves dropped
# speedup vs baseline: 1.0164x; 1.0060x over previous
.LBB0_151:
	s_andn2_b64 vcc, exec, s[0:1]
	s_cbranch_vccnz .LBB0_153
	s_lshr_b32 s0, s75, 3
	s_mulk_i32 s0, 0x880
	s_lshl_b32 s1, s75, 8
	s_and_b32 s1, s1, 0x700
	s_add_i32 s0, s0, s66
	s_add_i32 s0, s0, s1
	v_or_b32_e32 v152, s0, v176
	s_lshl_b32 s0, s69, 8
	v_lshl_or_b32 v0, v175, 3, s0
	v_or_b32_e32 v154, s61, v0
	s_nop 0
	v_and_b32_e32 v0, 0x7e, v154
	v_lshlrev_b32_e32 v0, 2, v0
	v_lshl_add_u64 v[170:171], s[42:43], 0, v[0:1]
	v_mul_hi_i32 v0, v152, s63
	v_lshrrev_b32_e32 v130, 31, v0
	v_ashrrev_i32_e32 v0, 10, v0
	v_add_u32_e32 v0, v0, v130
	v_mul_i32_i24_e32 v0, 0x880, v0
	v_sub_u32_e32 v166, v152, v0
	v_ashrrev_i32_e32 v167, 31, v166
	v_lshlrev_b64 v[130:131], 9, v[166:167]
	v_add_u32_e32 v153, 16, v152
	v_lshl_add_u64 v[130:131], v[170:171], 0, v[130:131]
	v_mul_hi_i32 v0, v153, s63
	global_load_dwordx4 v[178:181], v[130:131], off offset:16
	global_load_dwordx4 v[182:185], v[130:131], off
	v_lshrrev_b32_e32 v130, 31, v0
	v_ashrrev_i32_e32 v0, 10, v0
	v_add_u32_e32 v0, v0, v130
	v_mul_i32_i24_e32 v0, 0x880, v0
	v_sub_u32_e32 v198, v153, v0
	v_ashrrev_i32_e32 v199, 31, v198
	v_lshlrev_b64 v[130:131], 9, v[198:199]
	v_add_u32_e32 v177, 32, v152
	v_lshl_add_u64 v[130:131], v[170:171], 0, v[130:131]
	v_mul_hi_i32 v0, v177, s63
	global_load_dwordx4 v[186:189], v[130:131], off offset:16
	global_load_dwordx4 v[190:193], v[130:131], off
	v_lshrrev_b32_e32 v130, 31, v0
	v_ashrrev_i32_e32 v0, 10, v0
	v_add_u32_e32 v0, v0, v130
	v_mul_i32_i24_e32 v0, 0x880, v0
	v_sub_u32_e32 v200, v177, v0
	v_ashrrev_i32_e32 v201, 31, v200
	v_lshlrev_b64 v[130:131], 9, v[200:201]
	v_add_u32_e32 v201, 48, v152
	v_lshl_add_u64 v[130:131], v[170:171], 0, v[130:131]
	v_mul_hi_i32 v0, v201, s63
	global_load_dwordx4 v[138:141], v[130:131], off offset:16
	global_load_dwordx4 v[142:145], v[130:131], off
	v_lshrrev_b32_e32 v130, 31, v0
	v_ashrrev_i32_e32 v0, 10, v0
	v_add_u32_e32 v0, v0, v130
	v_mul_i32_i24_e32 v0, 0x880, v0
	v_sub_u32_e32 v172, v201, v0
	v_ashrrev_i32_e32 v173, 31, v172
	v_lshlrev_b64 v[130:131], 9, v[172:173]
	v_lshl_add_u64 v[134:135], v[170:171], 0, v[130:131]
	global_load_dwordx4 v[130:133], v[134:135], off offset:16
	s_nop 0
	global_load_dwordx4 v[134:137], v[134:135], off
	s_waitcnt vmcnt(0)
	v_mul_f32_e32 v204, v122, v179
	v_mul_f32_e32 v205, v123, v179
	v_cmp_lt_i32_e32 vcc, s11, v166
	v_fma_f32 v206, v122, v178, -v205
	v_fma_f32 v205, v123, v178, v204
	v_mul_f32_e32 v166, v126, v183
	v_mul_f32_e32 v167, v127, v183
	v_mov_b32_e32 v204, v181
	v_mul_f32_e32 v208, v124, v204
	v_mul_f32_e32 v209, v125, v204
	v_fma_f32 v168, v126, v182, -v167
	v_fma_f32 v167, v127, v182, v166
	v_mov_b32_e32 v202, v185
	v_fma_f32 v212, v124, v180, -v209
	v_fma_f32 v209, v125, v180, v208
	v_cndmask_b32_e32 v0, 0, v231, vcc
	v_mul_f32_e32 v194, v128, v202
	v_mul_f32_e32 v195, v129, v202
	v_mov_b32_e32 v169, v167
	v_mov_b32_e32 v213, v209
	s_movk_i32 s0, 0x1bff
	v_fma_f32 v196, v128, v184, -v195
	v_fma_f32 v195, v129, v184, v194
	v_mul_f32_e32 v216, v0, v168
	v_mul_f32_e32 v217, v0, v169
	v_mov_b32_e32 v207, v205
	v_mul_f32_e32 v222, v0, v212
	v_mul_f32_e32 v223, v0, v213
	v_cmp_lt_i32_e64 s[0:1], s0, v154
	v_mov_b32_e32 v197, v195
	v_mul_f32_e32 v220, v0, v206
	v_mul_f32_e32 v221, v0, v207
	v_cndmask_b32_e64 v155, v209, v223, s[0:1]
	v_cndmask_b32_e64 v166, v212, v222, s[0:1]
	v_cndmask_b32_e64 v167, v167, v217, s[0:1]
	v_cndmask_b32_e64 v168, v168, v216, s[0:1]
	v_mul_f32_e32 v218, v0, v196
	v_mul_f32_e32 v219, v0, v197
	v_cndmask_b32_e64 v169, v205, v221, s[0:1]
	v_cndmask_b32_e64 v173, v206, v220, s[0:1]
	v_cvt_pk_bf16_f32 v194, v168, v167
	v_cvt_pk_bf16_f32 v197, v166, v155
	v_mov_b64_e32 v[166:167], s[8:9]
	v_ashrrev_i32_e32 v155, 31, v154
	v_cndmask_b32_e64 v181, v195, v219, s[0:1]
	v_cndmask_b32_e64 v185, v196, v218, s[0:1]
	v_cvt_pk_bf16_f32 v196, v173, v169
	v_mad_i64_i32 v[206:207], s[6:7], v152, s47, v[166:167]
	v_lshlrev_b64 v[168:169], 1, v[154:155]
	v_cvt_pk_bf16_f32 v195, v185, v181
	v_lshl_add_u64 v[206:207], v[206:207], 0, v[168:169]
	global_store_dwordx4 v[206:207], v[194:197], off
	s_nop 1
	v_mul_f32_e32 v194, v118, v183
	v_mul_f32_e32 v195, v119, v183
	s_movk_i32 s6, 0x1b7f
	v_fma_f32 v196, v118, v182, -v195
	v_fma_f32 v183, v119, v182, v194
	v_mul_f32_e32 v194, v120, v202
	v_mul_f32_e32 v195, v121, v202
	v_mov_b32_e32 v197, v183
	v_fma_f32 v202, v120, v184, -v195
	v_fma_f32 v185, v121, v184, v194
	v_mul_f32_e32 v194, v110, v179
	v_mul_f32_e32 v195, v111, v179
	v_mov_b32_e32 v203, v185
	v_fma_f32 v208, v110, v178, -v195
	v_fma_f32 v179, v111, v178, v194
	v_mul_f32_e32 v194, v112, v204
	v_mul_f32_e32 v195, v113, v204
	v_mov_b32_e32 v209, v179
	v_fma_f32 v204, v112, v180, -v195
	v_fma_f32 v181, v113, v180, v194
	v_cmp_lt_i32_e32 vcc, s6, v154
	v_mov_b32_e32 v205, v181
	v_mul_f32_e32 v154, v0, v196
	v_mul_f32_e32 v155, v0, v197
	v_mul_f32_e32 v194, v0, v202
	v_mul_f32_e32 v195, v0, v203
	v_mul_f32_e32 v212, v0, v208
	v_mul_f32_e32 v213, v0, v209
	v_mul_f32_e32 v216, v0, v204
	v_mul_f32_e32 v217, v0, v205
	v_cndmask_b32_e32 v0, v181, v217, vcc
	v_cndmask_b32_e32 v173, v204, v216, vcc
	v_cndmask_b32_e32 v180, v179, v213, vcc
	v_cndmask_b32_e32 v181, v208, v212, vcc
	v_cndmask_b32_e32 v179, v185, v195, vcc
	v_cndmask_b32_e32 v182, v202, v194, vcc
	v_cndmask_b32_e32 v155, v183, v155, vcc
	v_cndmask_b32_e32 v154, v196, v154, vcc
	v_cvt_pk_bf16_f32 v178, v154, v155
	v_cvt_pk_bf16_f32 v179, v182, v179
	v_cvt_pk_bf16_f32 v180, v181, v180
	v_cvt_pk_bf16_f32 v181, v173, v0
	global_store_dwordx4 v[206:207], v[178:181], off offset:256
	v_mul_f32_e32 v154, v114, v191
	v_mul_f32_e32 v155, v115, v191
	v_mul_f32_e32 v184, v106, v187
	v_mul_f32_e32 v185, v107, v187
	v_fma_f32 v178, v114, v190, -v155
	v_fma_f32 v155, v115, v190, v154
	v_fma_f32 v194, v106, v186, -v185
	v_fma_f32 v185, v107, v186, v184
	v_mov_b32_e32 v154, v193
	v_mov_b32_e32 v184, v189
	v_mul_f32_e32 v180, v116, v154
	v_mul_f32_e32 v181, v117, v154
	v_mul_f32_e32 v196, v108, v184
	v_mul_f32_e32 v197, v109, v184
	v_cmp_lt_i32_e64 s[38:39], s11, v198
	v_fma_f32 v182, v116, v192, -v181
	v_fma_f32 v181, v117, v192, v180
	v_fma_f32 v198, v108, v188, -v197
	v_fma_f32 v197, v109, v188, v196
	v_cndmask_b32_e64 v0, 0, v231, s[38:39]
	v_mov_b32_e32 v183, v181
	v_mov_b32_e32 v199, v197
	v_mov_b32_e32 v179, v155
	v_mul_f32_e32 v204, v0, v182
	v_mul_f32_e32 v205, v0, v183
	v_mov_b32_e32 v195, v185
	v_mul_f32_e32 v208, v0, v198
	v_mul_f32_e32 v209, v0, v199
	v_mul_f32_e32 v202, v0, v178
	v_mul_f32_e32 v203, v0, v179
	v_mul_f32_e32 v206, v0, v194
	v_mul_f32_e32 v207, v0, v195
	v_cndmask_b32_e64 v173, v197, v209, s[0:1]
	v_cndmask_b32_e64 v183, v198, v208, s[0:1]
	v_cndmask_b32_e64 v179, v181, v205, s[0:1]
	v_cndmask_b32_e64 v181, v182, v204, s[0:1]
	v_cndmask_b32_e64 v180, v185, v207, s[0:1]
	v_cndmask_b32_e64 v185, v194, v206, s[0:1]
	v_cndmask_b32_e64 v155, v155, v203, s[0:1]
	v_cndmask_b32_e64 v178, v178, v202, s[0:1]
	v_cvt_pk_bf16_f32 v179, v181, v179
	v_cvt_pk_bf16_f32 v181, v183, v173
	v_mad_i64_i32 v[182:183], s[6:7], v153, s47, v[166:167]
	v_cvt_pk_bf16_f32 v178, v178, v155
	v_cvt_pk_bf16_f32 v180, v185, v180
	v_lshl_add_u64 v[182:183], v[182:183], 0, v[168:169]
	global_store_dwordx4 v[182:183], v[178:181], off
	s_nop 1
	v_mul_f32_e32 v178, v102, v191
	v_mul_f32_e32 v179, v103, v191
	v_mul_f32_e32 v155, v105, v154
	v_mul_f32_e32 v154, v104, v154
	v_fma_f32 v180, v102, v190, -v179
	v_fma_f32 v179, v103, v190, v178
	v_fma_f32 v190, v104, v192, -v155
	v_fma_f32 v155, v105, v192, v154
	v_mul_f32_e32 v192, v94, v187
	v_mul_f32_e32 v193, v95, v187
	v_mul_f32_e32 v185, v97, v184
	v_mul_f32_e32 v184, v96, v184
	v_fma_f32 v194, v94, v186, -v193
	v_fma_f32 v187, v95, v186, v192
	v_fma_f32 v192, v96, v188, -v185
	v_fma_f32 v185, v97, v188, v184
	v_mov_b32_e32 v181, v179
	v_mov_b32_e32 v191, v155
	v_mov_b32_e32 v195, v187
	v_mov_b32_e32 v193, v185
	v_mul_f32_e32 v188, v0, v180
	v_mul_f32_e32 v189, v0, v181
	v_mul_f32_e32 v196, v0, v190
	v_mul_f32_e32 v197, v0, v191
	v_mul_f32_e32 v198, v0, v194
	v_mul_f32_e32 v199, v0, v195
	v_mul_f32_e32 v202, v0, v192
	v_mul_f32_e32 v203, v0, v193
	v_cndmask_b32_e32 v0, v185, v203, vcc
	v_cndmask_b32_e32 v153, v192, v202, vcc
	v_cndmask_b32_e32 v154, v187, v199, vcc
	v_cndmask_b32_e32 v173, v194, v198, vcc
	v_cndmask_b32_e32 v155, v155, v197, vcc
	v_cndmask_b32_e32 v181, v190, v196, vcc
	v_cndmask_b32_e32 v178, v179, v189, vcc
	v_cndmask_b32_e32 v179, v180, v188, vcc
	v_cvt_pk_bf16_f32 v178, v179, v178
	v_cvt_pk_bf16_f32 v179, v181, v155
	v_cvt_pk_bf16_f32 v180, v173, v154
	v_cvt_pk_bf16_f32 v181, v153, v0
	global_store_dwordx4 v[182:183], v[178:181], off offset:256
	v_mul_f32_e32 v154, v98, v143
	v_mul_f32_e32 v155, v99, v143
	v_mul_f32_e32 v184, v90, v139
	v_mul_f32_e32 v185, v91, v139
	v_fma_f32 v178, v98, v142, -v155
	v_fma_f32 v155, v99, v142, v154
	v_fma_f32 v186, v90, v138, -v185
	v_fma_f32 v185, v91, v138, v184
	v_mov_b32_e32 v154, v145
	v_mov_b32_e32 v184, v141
	v_mul_f32_e32 v180, v100, v154
	v_mul_f32_e32 v181, v101, v154
	v_mul_f32_e32 v188, v92, v184
	v_mul_f32_e32 v189, v93, v184
	v_cmp_lt_i32_e64 s[38:39], s11, v200
	v_fma_f32 v182, v100, v144, -v181
	v_fma_f32 v181, v101, v144, v180
	v_fma_f32 v190, v92, v140, -v189
	v_fma_f32 v189, v93, v140, v188
	v_cndmask_b32_e64 v0, 0, v231, s[38:39]
	v_mov_b32_e32 v179, v155
	v_mov_b32_e32 v183, v181
	v_mov_b32_e32 v187, v185
	v_mov_b32_e32 v191, v189
	v_mul_f32_e32 v192, v0, v178
	v_mul_f32_e32 v193, v0, v179
	v_mul_f32_e32 v194, v0, v182
	v_mul_f32_e32 v195, v0, v183
	v_mul_f32_e32 v196, v0, v186
	v_mul_f32_e32 v197, v0, v187
	v_mul_f32_e32 v198, v0, v190
	v_mul_f32_e32 v199, v0, v191
	v_cndmask_b32_e64 v141, v189, v199, s[0:1]
	v_cndmask_b32_e64 v145, v190, v198, s[0:1]
	v_cndmask_b32_e64 v153, v185, v197, s[0:1]
	v_cndmask_b32_e64 v173, v186, v196, s[0:1]
	v_cndmask_b32_e64 v179, v181, v195, s[0:1]
	v_cndmask_b32_e64 v180, v182, v194, s[0:1]
	v_cndmask_b32_e64 v155, v155, v193, s[0:1]
	v_cndmask_b32_e64 v178, v178, v192, s[0:1]
	v_mad_i64_i32 v[182:183], s[6:7], v177, s47, v[166:167]
	v_cvt_pk_bf16_f32 v178, v178, v155
	v_cvt_pk_bf16_f32 v179, v180, v179
	v_cvt_pk_bf16_f32 v180, v173, v153
	v_cvt_pk_bf16_f32 v181, v145, v141
	v_lshl_add_u64 v[182:183], v[182:183], 0, v[168:169]
	global_store_dwordx4 v[182:183], v[178:181], off
	s_nop 1
	v_mul_f32_e32 v178, v86, v143
	v_mul_f32_e32 v179, v87, v143
	v_mul_f32_e32 v155, v89, v154
	v_mul_f32_e32 v154, v88, v154
	v_fma_f32 v180, v86, v142, -v179
	v_fma_f32 v143, v87, v142, v178
	v_fma_f32 v178, v88, v144, -v155
	v_fma_f32 v145, v89, v144, v154
	v_mul_f32_e32 v154, v78, v139
	v_mul_f32_e32 v155, v79, v139
	v_mov_b32_e32 v181, v143
	v_fma_f32 v186, v78, v138, -v155
	v_fma_f32 v139, v79, v138, v154
	v_mul_f32_e32 v154, v80, v184
	v_mul_f32_e32 v155, v81, v184
	v_mov_b32_e32 v179, v145
	v_fma_f32 v184, v80, v140, -v155
	v_fma_f32 v141, v81, v140, v154
	v_mov_b32_e32 v187, v139
	v_mov_b32_e32 v185, v141
	v_mul_f32_e32 v154, v0, v180
	v_mul_f32_e32 v155, v0, v181
	v_mul_f32_e32 v188, v0, v178
	v_mul_f32_e32 v189, v0, v179
	v_mul_f32_e32 v190, v0, v186
	v_mul_f32_e32 v191, v0, v187
	v_mul_f32_e32 v192, v0, v184
	v_mul_f32_e32 v193, v0, v185
	v_cndmask_b32_e32 v0, v141, v193, vcc
	v_cndmask_b32_e32 v141, v184, v192, vcc
	v_cndmask_b32_e32 v140, v139, v191, vcc
	v_cndmask_b32_e32 v142, v186, v190, vcc
	v_cndmask_b32_e32 v139, v145, v189, vcc
	v_cndmask_b32_e32 v144, v178, v188, vcc
	v_cndmask_b32_e32 v138, v143, v155, vcc
	v_cndmask_b32_e32 v143, v180, v154, vcc
	v_cvt_pk_bf16_f32 v138, v143, v138
	v_cvt_pk_bf16_f32 v139, v144, v139
	v_cvt_pk_bf16_f32 v140, v142, v140
	v_cvt_pk_bf16_f32 v141, v141, v0
	global_store_dwordx4 v[182:183], v[138:141], off offset:256
	v_mov_b32_e32 v142, v137
	v_mul_f32_e32 v144, v84, v142
	v_mul_f32_e32 v145, v85, v142
	v_cmp_lt_i32_e64 s[38:39], s11, v172
	v_fma_f32 v154, v84, v136, -v145
	v_fma_f32 v145, v85, v136, v144
	v_mul_f32_e32 v138, v82, v135
	v_mul_f32_e32 v139, v83, v135
	v_mov_b32_e32 v144, v133
	v_mul_f32_e32 v172, v74, v131
	v_mul_f32_e32 v173, v75, v131
	v_mul_f32_e32 v180, v76, v144
	v_mul_f32_e32 v181, v77, v144
	v_fma_f32 v140, v82, v134, -v139
	v_fma_f32 v139, v83, v134, v138
	v_fma_f32 v178, v74, v130, -v173
	v_fma_f32 v173, v75, v130, v172
	v_fma_f32 v182, v76, v132, -v181
	v_fma_f32 v181, v77, v132, v180
	v_cndmask_b32_e64 v0, 0, v231, s[38:39]
	v_mov_b32_e32 v141, v139
	v_mov_b32_e32 v155, v145
	v_mov_b32_e32 v179, v173
	v_mov_b32_e32 v183, v181
	v_mul_f32_e32 v184, v0, v140
	v_mul_f32_e32 v185, v0, v141
	v_mul_f32_e32 v186, v0, v154
	v_mul_f32_e32 v187, v0, v155
	v_mul_f32_e32 v188, v0, v178
	v_mul_f32_e32 v189, v0, v179
	v_mul_f32_e32 v190, v0, v182
	v_mul_f32_e32 v191, v0, v183
	v_cndmask_b32_e64 v133, v181, v191, s[0:1]
	v_cndmask_b32_e64 v137, v182, v190, s[0:1]
	v_cndmask_b32_e64 v141, v173, v189, s[0:1]
	v_cndmask_b32_e64 v143, v178, v188, s[0:1]
	v_cndmask_b32_e64 v145, v145, v187, s[0:1]
	v_cndmask_b32_e64 v153, v154, v186, s[0:1]
	v_cndmask_b32_e64 v138, v139, v185, s[0:1]
	v_cndmask_b32_e64 v139, v140, v184, s[0:1]
	v_mad_i64_i32 v[154:155], s[6:7], v201, s47, v[166:167]
	v_cvt_pk_bf16_f32 v138, v139, v138
	v_cvt_pk_bf16_f32 v139, v153, v145
	v_cvt_pk_bf16_f32 v140, v143, v141
	v_cvt_pk_bf16_f32 v141, v137, v133
	v_lshl_add_u64 v[154:155], v[154:155], 0, v[168:169]
	global_store_dwordx4 v[154:155], v[138:141], off
	s_nop 1
	v_mul_f32_e32 v138, v70, v135
	v_mul_f32_e32 v139, v71, v135
	s_nop 0
	v_fma_f32 v140, v70, v134, -v139
	v_fma_f32 v135, v71, v134, v138
	v_mul_f32_e32 v138, v72, v142
	v_mul_f32_e32 v139, v73, v142
	v_mov_b32_e32 v141, v135
	v_fma_f32 v142, v72, v136, -v139
	v_fma_f32 v137, v73, v136, v138
	v_mul_f32_e32 v138, v66, v131
	v_mul_f32_e32 v139, v67, v131
	v_mov_b32_e32 v143, v137
	v_fma_f32 v172, v66, v130, -v139
	v_fma_f32 v131, v67, v130, v138
	v_mul_f32_e32 v138, v68, v144
	v_mul_f32_e32 v139, v69, v144
	v_mov_b32_e32 v173, v131
	v_fma_f32 v144, v68, v132, -v139
	v_fma_f32 v133, v69, v132, v138
	v_mul_f32_e32 v138, v0, v140
	v_mul_f32_e32 v139, v0, v141
	v_mov_b32_e32 v145, v133
	v_mul_f32_e32 v178, v0, v142
	v_mul_f32_e32 v179, v0, v143
	v_mul_f32_e32 v180, v0, v172
	v_mul_f32_e32 v181, v0, v173
	v_mul_f32_e32 v182, v0, v144
	v_mul_f32_e32 v183, v0, v145
	v_cndmask_b32_e32 v0, v133, v183, vcc
	v_cndmask_b32_e32 v133, v144, v182, vcc
	v_cndmask_b32_e32 v132, v131, v181, vcc
	v_cndmask_b32_e32 v134, v172, v180, vcc
	v_cndmask_b32_e32 v131, v137, v179, vcc
	v_cndmask_b32_e32 v136, v142, v178, vcc
	v_cndmask_b32_e32 v130, v135, v139, vcc
	v_cndmask_b32_e32 v135, v140, v138, vcc
	v_cvt_pk_bf16_f32 v130, v135, v130
	v_cvt_pk_bf16_f32 v131, v136, v131
	v_cvt_pk_bf16_f32 v132, v134, v132
	v_cvt_pk_bf16_f32 v133, v133, v0
	global_store_dwordx4 v[154:155], v[130:133], off offset:256
	v_add_u32_e32 v177, 0x80, v152
	v_mul_hi_i32 v0, v177, s63
	v_lshrrev_b32_e32 v130, 31, v0
	v_ashrrev_i32_e32 v0, 10, v0
	v_add_u32_e32 v0, v0, v130
	v_mul_i32_i24_e32 v0, 0x880, v0
	v_sub_u32_e32 v154, v177, v0
	v_ashrrev_i32_e32 v155, 31, v154
	v_lshlrev_b64 v[130:131], 9, v[154:155]
	v_add_u32_e32 v211, 0x90, v152
	v_lshl_add_u64 v[130:131], v[170:171], 0, v[130:131]
	v_mul_hi_i32 v0, v211, s63
	global_load_dwordx4 v[178:181], v[130:131], off offset:16
	global_load_dwordx4 v[182:185], v[130:131], off
	v_lshrrev_b32_e32 v130, 31, v0
	v_ashrrev_i32_e32 v0, 10, v0
	v_add_u32_e32 v0, v0, v130
	v_mul_i32_i24_e32 v0, 0x880, v0
	v_sub_u32_e32 v194, v211, v0
	v_ashrrev_i32_e32 v195, 31, v194
	v_lshlrev_b64 v[130:131], 9, v[194:195]
	v_add_u32_e32 v215, 0xa0, v152
	v_lshl_add_u64 v[130:131], v[170:171], 0, v[130:131]
	v_mul_hi_i32 v0, v215, s63
	global_load_dwordx4 v[186:189], v[130:131], off offset:16
	global_load_dwordx4 v[190:193], v[130:131], off
	v_lshrrev_b32_e32 v130, 31, v0
	v_ashrrev_i32_e32 v0, 10, v0
	v_add_u32_e32 v0, v0, v130
	v_mul_i32_i24_e32 v0, 0x880, v0
	v_sub_u32_e32 v196, v215, v0
	v_ashrrev_i32_e32 v197, 31, v196
	v_lshlrev_b64 v[130:131], 9, v[196:197]
	v_add_u32_e32 v222, 0xb0, v152
	v_lshl_add_u64 v[130:131], v[170:171], 0, v[130:131]
	v_mul_hi_i32 v0, v222, s63
	global_load_dwordx4 v[138:141], v[130:131], off offset:16
	global_load_dwordx4 v[142:145], v[130:131], off
	v_lshrrev_b32_e32 v130, 31, v0
	v_ashrrev_i32_e32 v0, 10, v0
	v_add_u32_e32 v0, v0, v130
	v_mul_i32_i24_e32 v0, 0x880, v0
	v_sub_u32_e32 v172, v222, v0
	v_ashrrev_i32_e32 v173, 31, v172
	v_lshlrev_b64 v[130:131], 9, v[172:173]
	v_lshl_add_u64 v[134:135], v[170:171], 0, v[130:131]
	global_load_dwordx4 v[130:133], v[134:135], off offset:16
	s_nop 0
	global_load_dwordx4 v[134:137], v[134:135], off
	s_waitcnt vmcnt(0)
	v_mov_b32_e32 v170, v185
	v_mul_f32_e32 v198, v64, v170
	v_mul_f32_e32 v199, v65, v170
	v_mul_f32_e32 v152, v62, v183
	v_mul_f32_e32 v153, v63, v183
	v_fma_f32 v200, v64, v184, -v199
	v_fma_f32 v199, v65, v184, v198
	v_mul_f32_e32 v202, v58, v179
	v_mul_f32_e32 v203, v59, v179
	v_mov_b32_e32 v198, v181
	v_mul_f32_e32 v206, v60, v198
	v_mul_f32_e32 v207, v61, v198
	v_cmp_lt_i32_e64 s[38:39], s11, v154
	v_fma_f32 v154, v62, v182, -v153
	v_fma_f32 v153, v63, v182, v152
	v_fma_f32 v204, v58, v178, -v203
	v_fma_f32 v203, v59, v178, v202
	v_fma_f32 v208, v60, v180, -v207
	v_fma_f32 v207, v61, v180, v206
	v_cndmask_b32_e64 v0, 0, v231, s[38:39]
	v_mov_b32_e32 v155, v153
	v_mov_b32_e32 v201, v199
	v_mov_b32_e32 v205, v203
	v_mov_b32_e32 v209, v207
	v_mul_f32_e32 v212, v0, v154
	v_mul_f32_e32 v213, v0, v155
	v_mul_f32_e32 v216, v0, v200
	v_mul_f32_e32 v217, v0, v201
	v_mul_f32_e32 v218, v0, v204
	v_mul_f32_e32 v219, v0, v205
	v_mul_f32_e32 v220, v0, v208
	v_mul_f32_e32 v221, v0, v209
	v_cndmask_b32_e64 v155, v207, v221, s[0:1]
	v_cndmask_b32_e64 v171, v208, v220, s[0:1]
	v_cndmask_b32_e64 v173, v203, v219, s[0:1]
	v_cndmask_b32_e64 v181, v204, v218, s[0:1]
	v_cndmask_b32_e64 v185, v199, v217, s[0:1]
	v_cndmask_b32_e64 v195, v200, v216, s[0:1]
	v_cndmask_b32_e64 v152, v153, v213, s[0:1]
	v_cndmask_b32_e64 v153, v154, v212, s[0:1]
	v_mad_i64_i32 v[200:201], s[6:7], v177, s47, v[166:167]
	v_cvt_pk_bf16_f32 v152, v153, v152
	v_cvt_pk_bf16_f32 v153, v195, v185
	v_cvt_pk_bf16_f32 v154, v181, v173
	v_cvt_pk_bf16_f32 v155, v171, v155
	v_lshl_add_u64 v[200:201], v[200:201], 0, v[168:169]
	global_store_dwordx4 v[200:201], v[152:155], off
	s_nop 1
	v_mul_f32_e32 v152, v54, v183
	v_mul_f32_e32 v153, v55, v183
	v_mul_f32_e32 v171, v57, v170
	v_mul_f32_e32 v170, v56, v170
	v_fma_f32 v154, v54, v182, -v153
	v_fma_f32 v153, v55, v182, v152
	v_fma_f32 v182, v56, v184, -v171
	v_fma_f32 v171, v57, v184, v170
	v_mul_f32_e32 v184, v46, v179
	v_mul_f32_e32 v185, v47, v179
	v_mov_b32_e32 v155, v153
	v_fma_f32 v202, v46, v178, -v185
	v_fma_f32 v179, v47, v178, v184
	v_mul_f32_e32 v184, v48, v198
	v_mul_f32_e32 v185, v49, v198
	v_mov_b32_e32 v183, v171
	v_fma_f32 v198, v48, v180, -v185
	v_fma_f32 v181, v49, v180, v184
	v_mov_b32_e32 v203, v179
	v_mov_b32_e32 v199, v181
	v_mul_f32_e32 v184, v0, v154
	v_mul_f32_e32 v185, v0, v155
	v_mul_f32_e32 v204, v0, v182
	v_mul_f32_e32 v205, v0, v183
	v_mul_f32_e32 v206, v0, v202
	v_mul_f32_e32 v207, v0, v203
	v_mul_f32_e32 v208, v0, v198
	v_mul_f32_e32 v209, v0, v199
	v_cndmask_b32_e32 v0, v181, v209, vcc
	v_cndmask_b32_e32 v155, v198, v208, vcc
	v_cndmask_b32_e32 v170, v179, v207, vcc
	v_cndmask_b32_e32 v173, v202, v206, vcc
	v_cndmask_b32_e32 v171, v171, v205, vcc
	v_cndmask_b32_e32 v177, v182, v204, vcc
	v_cndmask_b32_e32 v152, v153, v185, vcc
	v_cndmask_b32_e32 v153, v154, v184, vcc
	v_cvt_pk_bf16_f32 v152, v153, v152
	v_cvt_pk_bf16_f32 v153, v177, v171
	v_cvt_pk_bf16_f32 v154, v173, v170
	v_cvt_pk_bf16_f32 v155, v155, v0
	global_store_dwordx4 v[200:201], v[152:155], off offset:256
	v_mov_b32_e32 v170, v193
	v_mul_f32_e32 v178, v52, v170
	v_mul_f32_e32 v179, v53, v170
	v_mul_f32_e32 v152, v50, v191
	v_mul_f32_e32 v153, v51, v191
	v_fma_f32 v180, v52, v192, -v179
	v_fma_f32 v179, v53, v192, v178
	v_cmp_lt_i32_e64 s[38:39], s11, v194
	v_mov_b32_e32 v178, v189
	v_fma_f32 v154, v50, v190, -v153
	v_fma_f32 v153, v51, v190, v152
	v_mul_f32_e32 v182, v42, v187
	v_mul_f32_e32 v183, v43, v187
	v_mul_f32_e32 v194, v44, v178
	v_mul_f32_e32 v195, v45, v178
	v_cndmask_b32_e64 v0, 0, v231, s[38:39]
	v_fma_f32 v184, v42, v186, -v183
	v_fma_f32 v183, v43, v186, v182
	v_fma_f32 v198, v44, v188, -v195
	v_fma_f32 v195, v45, v188, v194
	v_mov_b32_e32 v155, v153
	v_mov_b32_e32 v181, v179
	v_mul_f32_e32 v200, v0, v154
	v_mul_f32_e32 v201, v0, v155
	v_mul_f32_e32 v202, v0, v180
	v_mul_f32_e32 v203, v0, v181
	v_mov_b32_e32 v185, v183
	v_mov_b32_e32 v199, v195
	v_mul_f32_e32 v204, v0, v184
	v_mul_f32_e32 v205, v0, v185
	v_mul_f32_e32 v206, v0, v198
	v_mul_f32_e32 v207, v0, v199
	v_cndmask_b32_e64 v179, v179, v203, s[0:1]
	v_cndmask_b32_e64 v180, v180, v202, s[0:1]
	v_cndmask_b32_e64 v152, v153, v201, s[0:1]
	v_cndmask_b32_e64 v153, v154, v200, s[0:1]
	v_cndmask_b32_e64 v155, v195, v207, s[0:1]
	v_cndmask_b32_e64 v171, v198, v206, s[0:1]
	v_cndmask_b32_e64 v173, v183, v205, s[0:1]
	v_cndmask_b32_e64 v177, v184, v204, s[0:1]
	v_cvt_pk_bf16_f32 v152, v153, v152
	v_cvt_pk_bf16_f32 v153, v180, v179
	v_mad_i64_i32 v[180:181], s[6:7], v211, s47, v[166:167]
	v_cvt_pk_bf16_f32 v154, v177, v173
	v_cvt_pk_bf16_f32 v155, v171, v155
	v_lshl_add_u64 v[180:181], v[180:181], 0, v[168:169]
	global_store_dwordx4 v[180:181], v[152:155], off
	s_nop 1
	v_mul_f32_e32 v152, v38, v191
	v_mul_f32_e32 v153, v39, v191
	v_mul_f32_e32 v171, v41, v170
	v_mul_f32_e32 v170, v40, v170
	v_mul_f32_e32 v184, v30, v187
	v_mul_f32_e32 v185, v31, v187
	v_mul_f32_e32 v179, v33, v178
	v_mul_f32_e32 v178, v32, v178
	v_fma_f32 v154, v38, v190, -v153
	v_fma_f32 v153, v39, v190, v152
	v_fma_f32 v182, v40, v192, -v171
	v_fma_f32 v171, v41, v192, v170
	v_fma_f32 v190, v30, v186, -v185
	v_fma_f32 v185, v31, v186, v184
	v_fma_f32 v186, v32, v188, -v179
	v_fma_f32 v179, v33, v188, v178
	v_mov_b32_e32 v155, v153
	v_mov_b32_e32 v183, v171
	v_mov_b32_e32 v191, v185
	v_mov_b32_e32 v187, v179
	v_mul_f32_e32 v188, v0, v154
	v_mul_f32_e32 v189, v0, v155
	v_mul_f32_e32 v192, v0, v182
	v_mul_f32_e32 v193, v0, v183
	v_mul_f32_e32 v194, v0, v190
	v_mul_f32_e32 v195, v0, v191
	v_mul_f32_e32 v198, v0, v186
	v_mul_f32_e32 v199, v0, v187
	v_cndmask_b32_e32 v0, v179, v199, vcc
	v_cndmask_b32_e32 v155, v186, v198, vcc
	v_cndmask_b32_e32 v170, v185, v195, vcc
	v_cndmask_b32_e32 v173, v190, v194, vcc
	v_cndmask_b32_e32 v171, v171, v193, vcc
	v_cndmask_b32_e32 v177, v182, v192, vcc
	v_cndmask_b32_e32 v152, v153, v189, vcc
	v_cndmask_b32_e32 v153, v154, v188, vcc
	v_cvt_pk_bf16_f32 v152, v153, v152
	v_cvt_pk_bf16_f32 v153, v177, v171
	v_cvt_pk_bf16_f32 v154, v173, v170
	v_cvt_pk_bf16_f32 v155, v155, v0
	global_store_dwordx4 v[180:181], v[152:155], off offset:256
	v_mov_b32_e32 v170, v145
	v_mul_f32_e32 v178, v36, v170
	v_mul_f32_e32 v179, v37, v170
	v_mul_f32_e32 v152, v34, v143
	v_mul_f32_e32 v153, v35, v143
	v_fma_f32 v180, v36, v144, -v179
	v_fma_f32 v179, v37, v144, v178
	v_mul_f32_e32 v182, v26, v139
	v_mul_f32_e32 v183, v27, v139
	v_mov_b32_e32 v178, v141
	v_mul_f32_e32 v186, v28, v178
	v_mul_f32_e32 v187, v29, v178
	v_cmp_lt_i32_e64 s[38:39], s11, v196
	v_fma_f32 v154, v34, v142, -v153
	v_fma_f32 v153, v35, v142, v152
	v_fma_f32 v184, v26, v138, -v183
	v_fma_f32 v183, v27, v138, v182
	v_fma_f32 v188, v28, v140, -v187
	v_fma_f32 v187, v29, v140, v186
	v_cndmask_b32_e64 v0, 0, v231, s[38:39]
	v_mov_b32_e32 v155, v153
	v_mov_b32_e32 v181, v179
	v_mov_b32_e32 v185, v183
	v_mov_b32_e32 v189, v187
	v_mul_f32_e32 v190, v0, v154
	v_mul_f32_e32 v191, v0, v155
	v_mul_f32_e32 v192, v0, v180
	v_mul_f32_e32 v193, v0, v181
	v_mul_f32_e32 v194, v0, v184
	v_mul_f32_e32 v195, v0, v185
	v_mul_f32_e32 v196, v0, v188
	v_mul_f32_e32 v197, v0, v189
	v_cndmask_b32_e64 v141, v187, v197, s[0:1]
	v_cndmask_b32_e64 v145, v188, v196, s[0:1]
	v_cndmask_b32_e64 v155, v183, v195, s[0:1]
	v_cndmask_b32_e64 v171, v184, v194, s[0:1]
	v_cndmask_b32_e64 v173, v179, v193, s[0:1]
	v_cndmask_b32_e64 v177, v180, v192, s[0:1]
	v_cndmask_b32_e64 v152, v153, v191, s[0:1]
	v_cndmask_b32_e64 v153, v154, v190, s[0:1]
	v_mad_i64_i32 v[180:181], s[6:7], v215, s47, v[166:167]
	v_cvt_pk_bf16_f32 v152, v153, v152
	v_cvt_pk_bf16_f32 v153, v177, v173
	v_cvt_pk_bf16_f32 v154, v171, v155
	v_cvt_pk_bf16_f32 v155, v145, v141
	v_lshl_add_u64 v[180:181], v[180:181], 0, v[168:169]
	global_store_dwordx4 v[180:181], v[152:155], off
	s_nop 1
	v_mul_f32_e32 v152, v22, v143
	v_mul_f32_e32 v153, v23, v143
	s_nop 0
	v_fma_f32 v154, v22, v142, -v153
	v_fma_f32 v143, v23, v142, v152
	v_mul_f32_e32 v152, v24, v170
	v_mul_f32_e32 v153, v25, v170
	v_mov_b32_e32 v155, v143
	v_fma_f32 v170, v24, v144, -v153
	v_fma_f32 v145, v25, v144, v152
	v_mul_f32_e32 v152, v14, v139
	v_mul_f32_e32 v153, v15, v139
	v_mov_b32_e32 v171, v145
	v_fma_f32 v182, v14, v138, -v153
	v_fma_f32 v139, v15, v138, v152
	v_mul_f32_e32 v152, v16, v178
	v_mul_f32_e32 v153, v17, v178
	v_mov_b32_e32 v183, v139
	v_fma_f32 v178, v16, v140, -v153
	v_fma_f32 v141, v17, v140, v152
	v_mul_f32_e32 v152, v0, v154
	v_mul_f32_e32 v153, v0, v155
	v_mov_b32_e32 v179, v141
	v_mul_f32_e32 v184, v0, v170
	v_mul_f32_e32 v185, v0, v171
	v_mul_f32_e32 v186, v0, v182
	v_mul_f32_e32 v187, v0, v183
	v_mul_f32_e32 v188, v0, v178
	v_mul_f32_e32 v189, v0, v179
	v_cndmask_b32_e32 v0, v141, v189, vcc
	v_cndmask_b32_e32 v141, v178, v188, vcc
	v_cndmask_b32_e32 v140, v139, v187, vcc
	v_cndmask_b32_e32 v142, v182, v186, vcc
	v_cndmask_b32_e32 v139, v145, v185, vcc
	v_cndmask_b32_e32 v144, v170, v184, vcc
	v_cndmask_b32_e32 v138, v143, v153, vcc
	v_cndmask_b32_e32 v143, v154, v152, vcc
	v_cvt_pk_bf16_f32 v138, v143, v138
	v_cvt_pk_bf16_f32 v139, v144, v139
	v_cvt_pk_bf16_f32 v140, v142, v140
	v_cvt_pk_bf16_f32 v141, v141, v0
	global_store_dwordx4 v[180:181], v[138:141], off offset:256
	v_mov_b32_e32 v142, v137
	v_mul_f32_e32 v144, v20, v142
	v_mul_f32_e32 v145, v21, v142
	v_mul_f32_e32 v138, v18, v135
	v_mul_f32_e32 v139, v19, v135
	v_fma_f32 v152, v20, v136, -v145
	v_fma_f32 v145, v21, v136, v144
	v_cmp_lt_i32_e64 s[38:39], s11, v172
	v_mov_b32_e32 v144, v133
	v_fma_f32 v140, v18, v134, -v139
	v_fma_f32 v139, v19, v134, v138
	v_mul_f32_e32 v154, v10, v131
	v_mul_f32_e32 v155, v11, v131
	v_mul_f32_e32 v172, v12, v144
	v_mul_f32_e32 v173, v13, v144
	v_cndmask_b32_e64 v0, 0, v231, s[38:39]
	v_fma_f32 v170, v10, v130, -v155
	v_fma_f32 v155, v11, v130, v154
	v_fma_f32 v178, v12, v132, -v173
	v_fma_f32 v252, v12, v132, v173
	v_fma_f32 v173, v13, v132, v172
	v_mov_b32_e32 v172, v252
	v_mov_b32_e32 v141, v139
	v_mov_b32_e32 v153, v145
	v_mul_f32_e32 v180, v0, v140
	v_mul_f32_e32 v181, v0, v141
	v_mul_f32_e32 v182, v0, v152
	v_mul_f32_e32 v183, v0, v153
	v_mov_b32_e32 v171, v155
	v_mov_b32_e32 v179, v173
	v_mul_f32_e32 v184, v0, v170
	v_mul_f32_e32 v185, v0, v171
	v_mul_f32_e32 v186, v0, v178
	v_mul_f32_e32 v187, v0, v179
	v_cndmask_b32_e64 v145, v145, v183, s[0:1]
	v_cndmask_b32_e64 v152, v152, v182, s[0:1]
	v_cndmask_b32_e64 v138, v139, v181, s[0:1]
	v_cndmask_b32_e64 v139, v140, v180, s[0:1]
	v_cndmask_b32_e64 v133, v173, v187, s[0:1]
	v_cndmask_b32_e64 v137, v178, v186, s[0:1]
	v_cndmask_b32_e64 v141, v155, v185, s[0:1]
	v_cndmask_b32_e64 v143, v170, v184, s[0:1]
	v_cvt_pk_bf16_f32 v138, v139, v138
	v_cvt_pk_bf16_f32 v139, v152, v145
	v_mad_i64_i32 v[152:153], s[0:1], v222, s47, v[166:167]
	v_cvt_pk_bf16_f32 v140, v143, v141
	v_cvt_pk_bf16_f32 v141, v137, v133
	v_lshl_add_u64 v[152:153], v[152:153], 0, v[168:169]
	global_store_dwordx4 v[152:153], v[138:141], off
	s_nop 1
	v_mul_f32_e32 v138, v6, v135
	v_mul_f32_e32 v139, v7, v135
	s_nop 0
	v_fma_f32 v140, v6, v134, -v139
	v_fma_f32 v135, v7, v134, v138
	v_mul_f32_e32 v138, v8, v142
	v_mul_f32_e32 v139, v9, v142
	v_mov_b32_e32 v141, v135
	v_fma_f32 v142, v8, v136, -v139
	v_fma_f32 v137, v9, v136, v138
	v_mul_f32_e32 v138, v2, v131
	v_mul_f32_e32 v139, v3, v131
	v_mov_b32_e32 v143, v137
	v_fma_f32 v154, v2, v130, -v139
	v_fma_f32 v131, v3, v130, v138
	v_mul_f32_e32 v138, v4, v144
	v_mul_f32_e32 v139, v5, v144
	v_mov_b32_e32 v155, v131
	v_fma_f32 v144, v4, v132, -v139
	v_fma_f32 v133, v5, v132, v138
	v_mul_f32_e32 v138, v0, v140
	v_mul_f32_e32 v139, v0, v141
	v_mov_b32_e32 v145, v133
	v_mul_f32_e32 v166, v0, v142
	v_mul_f32_e32 v167, v0, v143
	v_mul_f32_e32 v168, v0, v154
	v_mul_f32_e32 v169, v0, v155
	v_mul_f32_e32 v170, v0, v144
	v_mul_f32_e32 v171, v0, v145
	v_cndmask_b32_e32 v0, v133, v171, vcc
	v_cndmask_b32_e32 v133, v144, v170, vcc
	v_cndmask_b32_e32 v132, v131, v169, vcc
	v_cndmask_b32_e32 v134, v154, v168, vcc
	v_cndmask_b32_e32 v131, v137, v167, vcc
	v_cndmask_b32_e32 v136, v142, v166, vcc
	v_cndmask_b32_e32 v130, v135, v139, vcc
	v_cndmask_b32_e32 v135, v140, v138, vcc
	v_cvt_pk_bf16_f32 v130, v135, v130
	v_cvt_pk_bf16_f32 v131, v136, v131
	v_cvt_pk_bf16_f32 v132, v134, v132
	v_cvt_pk_bf16_f32 v133, v133, v0
	global_store_dwordx4 v[152:153], v[130:133], off offset:256

.LBB0_157:
	s_andn2_b64 vcc, exec, s[0:1]
	s_cbranch_vccnz .LBB0_128
	s_lshr_b32 s0, s75, 3
	s_mulk_i32 s0, 0x880
	s_lshl_b32 s1, s75, 8
	s_and_b32 s1, s1, 0x700
	s_add_i32 s0, s0, s66
	s_add_i32 s0, s0, s1
	v_or_b32_e32 v196, s0, v176
	s_lshl_b32 s0, s69, 8
	v_lshl_or_b32 v0, v175, 3, s0
	v_or_b32_e32 v144, s61, v0
	s_nop 0
	v_and_b32_e32 v0, 62, v144
	v_lshlrev_b32_e32 v0, 2, v0
	v_lshl_add_u64 v[130:131], s[28:29], 0, v[0:1]
	v_mul_hi_i32 v0, v196, s63
	v_lshrrev_b32_e32 v132, 31, v0
	v_ashrrev_i32_e32 v0, 10, v0
	v_add_u32_e32 v0, v0, v132
	v_mul_i32_i24_e32 v0, 0x880, v0
	v_add_u32_e32 v175, 16, v196
	v_sub_u32_e32 v132, v196, v0
	v_mul_hi_i32 v0, v175, s63
	v_lshrrev_b32_e32 v140, 31, v0
	v_ashrrev_i32_e32 v0, 10, v0
	v_add_u32_e32 v0, v0, v140
	v_mul_i32_i24_e32 v0, 0x880, v0
	v_add_u32_e32 v197, 32, v196
	v_sub_u32_e32 v140, v175, v0
	v_mul_hi_i32 v0, v197, s63
	v_lshrrev_b32_e32 v145, 31, v0
	v_ashrrev_i32_e32 v0, 10, v0
	v_add_u32_e32 v0, v0, v145
	v_mul_i32_i24_e32 v0, 0x880, v0
	v_add_u32_e32 v198, 48, v196
	v_sub_u32_e32 v166, v197, v0
	v_mul_hi_i32 v0, v198, s63
	v_lshrrev_b32_e32 v145, 31, v0
	v_ashrrev_i32_e32 v0, 10, v0
	v_add_u32_e32 v0, v0, v145
	v_mul_i32_i24_e32 v0, 0x880, v0
	v_sub_u32_e32 v176, v198, v0
	v_ashrrev_i32_e32 v133, 31, v132
	v_ashrrev_i32_e32 v141, 31, v140
	v_ashrrev_i32_e32 v167, 31, v166
	v_ashrrev_i32_e32 v177, 31, v176
	v_lshlrev_b64 v[132:133], 8, v[132:133]
	v_lshlrev_b64 v[140:141], 8, v[140:141]
	v_lshlrev_b64 v[166:167], 8, v[166:167]
	v_lshlrev_b64 v[176:177], 8, v[176:177]
	v_lshl_add_u64 v[136:137], v[130:131], 0, v[132:133]
	v_lshl_add_u64 v[152:153], v[130:131], 0, v[140:141]
	v_lshl_add_u64 v[170:171], v[130:131], 0, v[166:167]
	v_lshl_add_u64 v[180:181], v[130:131], 0, v[176:177]
	global_load_dwordx4 v[132:135], v[136:137], off offset:16
	s_nop 0
	global_load_dwordx4 v[136:139], v[136:137], off
	s_nop 0
	global_load_dwordx4 v[140:143], v[152:153], off offset:16
	s_nop 0
	global_load_dwordx4 v[152:155], v[152:153], off
	s_nop 0
	global_load_dwordx4 v[166:169], v[170:171], off offset:16
	s_nop 0
	global_load_dwordx4 v[170:173], v[170:171], off
	s_nop 0
	global_load_dwordx4 v[176:179], v[180:181], off offset:16
	s_nop 0
	global_load_dwordx4 v[180:183], v[180:181], off
	s_waitcnt vmcnt(0)
	v_mul_f32_e32 v184, v126, v137
	v_mul_f32_e32 v185, v127, v137
	v_mov_b32_e32 v0, v139
	v_fma_f32 v186, v126, v136, -v185
	v_fma_f32 v127, v127, v136, v184
	v_mul_f32_e32 v184, v128, v0
	v_mul_f32_e32 v185, v129, v0
	v_ashrrev_i32_e32 v145, 31, v144
	v_fma_f32 v188, v128, v138, -v185
	v_fma_f32 v189, v129, v139, -v184
	v_fma_f32 v129, v129, v138, v184
	v_mul_f32_e32 v184, v122, v133
	v_mul_f32_e32 v185, v123, v133
	v_cvt_pk_bf16_f32 v126, v186, v127
	v_fma_f32 v190, v122, v132, -v185
	v_fma_f32 v191, v123, v133, -v184
	v_fma_f32 v123, v123, v132, v184
	v_mov_b32_e32 v184, v135
	v_mul_f32_e32 v192, v124, v184
	v_mul_f32_e32 v193, v125, v184
	v_cvt_pk_bf16_f32 v128, v190, v123
	v_fma_f32 v194, v124, v134, -v193
	v_fma_f32 v195, v125, v135, -v192
	v_fma_f32 v125, v125, v134, v192
	v_mov_b64_e32 v[122:123], s[8:9]
	v_cvt_pk_bf16_f32 v127, v188, v129
	v_cvt_pk_bf16_f32 v129, v194, v125
	v_mad_i64_i32 v[186:187], s[0:1], v196, s47, v[122:123]
	v_lshlrev_b64 v[124:125], 1, v[144:145]
	v_lshl_add_u64 v[144:145], v[186:187], 0, v[124:125]
	global_store_dwordx4 v[144:145], v[126:129], off
	s_nop 1
	v_mul_f32_e32 v126, v118, v137
	v_mul_f32_e32 v127, v119, v137
	s_nop 0
	v_fma_f32 v128, v118, v136, -v127
	v_fma_f32 v129, v119, v137, -v126
	v_fma_f32 v119, v119, v136, v126
	v_mul_f32_e32 v126, v120, v0
	v_mul_f32_e32 v127, v121, v0
	s_nop 0
	v_fma_f32 v136, v120, v138, -v127
	v_fma_f32 v137, v121, v139, -v126
	v_fma_f32 v121, v121, v138, v126
	v_mul_f32_e32 v126, v110, v133
	v_mul_f32_e32 v127, v111, v133
	s_nop 0
	v_fma_f32 v138, v110, v132, -v127
	v_fma_f32 v139, v111, v133, -v126
	v_fma_f32 v127, v111, v132, v126
	v_mul_f32_e32 v110, v112, v184
	v_mul_f32_e32 v111, v113, v184
	s_nop 0
	v_fma_f32 v132, v112, v134, -v111
	v_fma_f32 v133, v113, v135, -v110
	v_fma_f32 v113, v113, v134, v110
	v_cvt_pk_bf16_f32 v110, v128, v119
	v_cvt_pk_bf16_f32 v111, v136, v121
	v_cvt_pk_bf16_f32 v112, v138, v127
	v_cvt_pk_bf16_f32 v113, v132, v113
	global_store_dwordx4 v[144:145], v[110:113], off offset:256
	s_nop 1
	v_mul_f32_e32 v110, v114, v153
	v_mul_f32_e32 v111, v115, v153
	v_mov_b32_e32 v0, v155
	v_fma_f32 v112, v114, v152, -v111
	v_fma_f32 v111, v115, v152, v110
	v_mul_f32_e32 v114, v116, v0
	v_mul_f32_e32 v115, v117, v0
	v_mov_b32_e32 v110, v143
	v_fma_f32 v118, v116, v154, -v115
	v_fma_f32 v119, v117, v155, -v114
	v_fma_f32 v115, v117, v154, v114
	v_mul_f32_e32 v116, v106, v141
	v_mul_f32_e32 v117, v107, v141
	s_nop 0
	v_fma_f32 v120, v106, v140, -v117
	v_fma_f32 v121, v107, v141, -v116
	v_fma_f32 v117, v107, v140, v116
	v_mul_f32_e32 v106, v108, v110
	v_mul_f32_e32 v107, v109, v110
	s_nop 0
	v_fma_f32 v126, v108, v142, -v107
	v_fma_f32 v127, v109, v143, -v106
	v_fma_f32 v109, v109, v142, v106
	v_cvt_pk_bf16_f32 v106, v112, v111
	v_mad_i64_i32 v[112:113], s[0:1], v175, s47, v[122:123]
	v_cvt_pk_bf16_f32 v107, v118, v115
	v_cvt_pk_bf16_f32 v108, v120, v117
	v_cvt_pk_bf16_f32 v109, v126, v109
	v_lshl_add_u64 v[112:113], v[112:113], 0, v[124:125]
	global_store_dwordx4 v[112:113], v[106:109], off
	s_nop 1
	v_mul_f32_e32 v106, v102, v153
	v_mul_f32_e32 v107, v103, v153
	s_nop 0
	v_fma_f32 v108, v102, v152, -v107
	v_fma_f32 v103, v103, v152, v106
	v_mul_f32_e32 v106, v104, v0
	v_mul_f32_e32 v107, v105, v0
	s_nop 0
	v_fma_f32 v114, v104, v154, -v107
	v_fma_f32 v115, v105, v155, -v106
	v_fma_f32 v105, v105, v154, v106
	v_mul_f32_e32 v106, v94, v141
	v_mul_f32_e32 v107, v95, v141
	s_nop 0
	v_fma_f32 v116, v94, v140, -v107
	v_fma_f32 v117, v95, v141, -v106
	v_fma_f32 v107, v95, v140, v106
	v_mul_f32_e32 v94, v96, v110
	v_mul_f32_e32 v95, v97, v110
	s_nop 0
	v_fma_f32 v110, v96, v142, -v95
	v_fma_f32 v97, v97, v142, v94
	v_cvt_pk_bf16_f32 v94, v108, v103
	v_cvt_pk_bf16_f32 v95, v114, v105
	v_cvt_pk_bf16_f32 v96, v116, v107
	v_cvt_pk_bf16_f32 v97, v110, v97
	global_store_dwordx4 v[112:113], v[94:97], off offset:256
	s_nop 1
	v_mul_f32_e32 v94, v98, v171
	v_mul_f32_e32 v95, v99, v171
	v_mov_b32_e32 v0, v173
	v_fma_f32 v96, v98, v170, -v95
	v_fma_f32 v95, v99, v170, v94
	v_mul_f32_e32 v98, v100, v0
	v_mul_f32_e32 v99, v101, v0
	v_mov_b32_e32 v94, v169
	v_fma_f32 v102, v100, v172, -v99
	v_fma_f32 v99, v101, v172, v98
	v_mul_f32_e32 v100, v90, v167
	v_mul_f32_e32 v101, v91, v167
	s_nop 0
	v_fma_f32 v104, v90, v166, -v101
	v_fma_f32 v101, v91, v166, v100
	v_mul_f32_e32 v90, v92, v94
	v_mul_f32_e32 v91, v93, v94
	s_nop 0
	v_fma_f32 v106, v92, v168, -v91
	v_fma_f32 v93, v93, v168, v90
	v_cvt_pk_bf16_f32 v90, v96, v95
	v_mad_i64_i32 v[96:97], s[0:1], v197, s47, v[122:123]
	v_cvt_pk_bf16_f32 v91, v102, v99
	v_cvt_pk_bf16_f32 v92, v104, v101
	v_cvt_pk_bf16_f32 v93, v106, v93
	v_lshl_add_u64 v[96:97], v[96:97], 0, v[124:125]
	global_store_dwordx4 v[96:97], v[90:93], off
	s_nop 1
	v_mul_f32_e32 v90, v86, v171
	v_mul_f32_e32 v91, v87, v171
	s_nop 0
	v_fma_f32 v92, v86, v170, -v91
	v_fma_f32 v87, v87, v170, v90
	v_mul_f32_e32 v90, v88, v0
	v_mul_f32_e32 v91, v89, v0
	s_nop 0
	v_fma_f32 v98, v88, v172, -v91
	v_fma_f32 v89, v89, v172, v90
	v_mul_f32_e32 v90, v78, v167
	v_mul_f32_e32 v91, v79, v167
	s_nop 0
	v_fma_f32 v100, v78, v166, -v91
	v_fma_f32 v91, v79, v166, v90
	v_mul_f32_e32 v78, v80, v94
	v_mul_f32_e32 v79, v81, v94
	s_nop 0
	v_fma_f32 v94, v80, v168, -v79
	v_fma_f32 v81, v81, v168, v78
	v_cvt_pk_bf16_f32 v78, v92, v87
	v_cvt_pk_bf16_f32 v79, v98, v89
	v_cvt_pk_bf16_f32 v80, v100, v91
	v_cvt_pk_bf16_f32 v81, v94, v81
	global_store_dwordx4 v[96:97], v[78:81], off offset:256
	s_nop 1
	v_mul_f32_e32 v78, v82, v181
	v_mul_f32_e32 v79, v83, v181
	v_mov_b32_e32 v0, v183
	v_fma_f32 v80, v82, v180, -v79
	v_fma_f32 v79, v83, v180, v78
	v_mul_f32_e32 v82, v84, v0
	v_mul_f32_e32 v83, v85, v0
	v_mov_b32_e32 v78, v179
	v_fma_f32 v86, v84, v182, -v83
	v_fma_f32 v83, v85, v182, v82
	v_mul_f32_e32 v84, v74, v177
	v_mul_f32_e32 v85, v75, v177
	s_nop 0
	v_fma_f32 v88, v74, v176, -v85
	v_fma_f32 v85, v75, v176, v84
	v_mul_f32_e32 v74, v76, v78
	v_mul_f32_e32 v75, v77, v78
	s_nop 0
	v_fma_f32 v90, v76, v178, -v75
	v_fma_f32 v77, v77, v178, v74
	v_cvt_pk_bf16_f32 v74, v80, v79
	v_mad_i64_i32 v[80:81], s[0:1], v198, s47, v[122:123]
	v_cvt_pk_bf16_f32 v75, v86, v83
	v_cvt_pk_bf16_f32 v76, v88, v85
	v_cvt_pk_bf16_f32 v77, v90, v77
	v_lshl_add_u64 v[80:81], v[80:81], 0, v[124:125]
	global_store_dwordx4 v[80:81], v[74:77], off
	s_nop 1
	v_mul_f32_e32 v74, v70, v181
	v_mul_f32_e32 v75, v71, v181
	s_nop 0
	v_fma_f32 v76, v70, v180, -v75
	v_fma_f32 v71, v71, v180, v74
	v_mul_f32_e32 v74, v72, v0
	v_mul_f32_e32 v75, v73, v0
	s_nop 0
	v_fma_f32 v82, v72, v182, -v75
	v_fma_f32 v73, v73, v182, v74
	v_mul_f32_e32 v74, v66, v177
	v_mul_f32_e32 v75, v67, v177
	s_nop 0
	v_fma_f32 v84, v66, v176, -v75
	v_fma_f32 v75, v67, v176, v74
	v_mul_f32_e32 v66, v68, v78
	v_mul_f32_e32 v67, v69, v78
	s_nop 0
	v_fma_f32 v78, v68, v178, -v67
	v_fma_f32 v69, v69, v178, v66
	v_cvt_pk_bf16_f32 v66, v76, v71
	v_cvt_pk_bf16_f32 v67, v82, v73
	v_cvt_pk_bf16_f32 v68, v84, v75
	v_cvt_pk_bf16_f32 v69, v78, v69
	global_store_dwordx4 v[80:81], v[66:69], off offset:256
	v_add_u32_e32 v108, 0x80, v196
	v_mul_hi_i32 v0, v108, s63
	v_lshrrev_b32_e32 v66, 31, v0
	v_ashrrev_i32_e32 v0, 10, v0
	v_add_u32_e32 v0, v0, v66
	v_mul_i32_i24_e32 v0, 0x880, v0
	v_add_u32_e32 v109, 0x90, v196
	v_sub_u32_e32 v66, v108, v0
	v_mul_hi_i32 v0, v109, s63
	v_lshrrev_b32_e32 v74, 31, v0
	v_ashrrev_i32_e32 v0, 10, v0
	v_add_u32_e32 v0, v0, v74
	v_mul_i32_i24_e32 v0, 0x880, v0
	v_add_u32_e32 v110, 0xa0, v196
	v_sub_u32_e32 v74, v109, v0
	v_mul_hi_i32 v0, v110, s63
	v_lshrrev_b32_e32 v82, 31, v0
	v_ashrrev_i32_e32 v0, 10, v0
	v_add_u32_e32 v0, v0, v82
	v_mul_i32_i24_e32 v0, 0x880, v0
	v_add_u32_e32 v111, 0xb0, v196
	v_sub_u32_e32 v82, v110, v0
	v_mul_hi_i32 v0, v111, s63
	v_lshrrev_b32_e32 v90, 31, v0
	v_ashrrev_i32_e32 v0, 10, v0
	v_add_u32_e32 v0, v0, v90
	v_mul_i32_i24_e32 v0, 0x880, v0
	v_sub_u32_e32 v90, v111, v0
	v_ashrrev_i32_e32 v67, 31, v66
	v_ashrrev_i32_e32 v75, 31, v74
	v_ashrrev_i32_e32 v83, 31, v82
	v_ashrrev_i32_e32 v91, 31, v90
	v_lshlrev_b64 v[66:67], 8, v[66:67]
	v_lshlrev_b64 v[74:75], 8, v[74:75]
	v_lshlrev_b64 v[82:83], 8, v[82:83]
	v_lshlrev_b64 v[90:91], 8, v[90:91]
	v_lshl_add_u64 v[70:71], v[130:131], 0, v[66:67]
	v_lshl_add_u64 v[78:79], v[130:131], 0, v[74:75]
	v_lshl_add_u64 v[86:87], v[130:131], 0, v[82:83]
	v_lshl_add_u64 v[94:95], v[130:131], 0, v[90:91]
	global_load_dwordx4 v[66:69], v[70:71], off offset:16
	s_nop 0
	global_load_dwordx4 v[70:73], v[70:71], off
	s_nop 0
	global_load_dwordx4 v[74:77], v[78:79], off offset:16
	s_nop 0
	global_load_dwordx4 v[78:81], v[78:79], off
	s_nop 0
	global_load_dwordx4 v[82:85], v[86:87], off offset:16
	s_nop 0
	global_load_dwordx4 v[86:89], v[86:87], off
	s_nop 0
	global_load_dwordx4 v[90:93], v[94:95], off offset:16
	s_nop 0
	global_load_dwordx4 v[94:97], v[94:95], off
	s_waitcnt vmcnt(0)
	v_mul_f32_e32 v98, v62, v71
	v_mul_f32_e32 v99, v63, v71
	v_mov_b32_e32 v0, v73
	v_fma_f32 v100, v62, v70, -v99
	v_fma_f32 v101, v63, v71, -v98
	v_fma_f32 v63, v63, v70, v98
	v_mul_f32_e32 v98, v64, v0
	v_mul_f32_e32 v99, v65, v0
	v_mov_b32_e32 v62, v69
	v_fma_f32 v102, v64, v72, -v99
	v_fma_f32 v103, v65, v73, -v98
	v_fma_f32 v65, v65, v72, v98
	v_mul_f32_e32 v98, v58, v67
	v_mul_f32_e32 v99, v59, v67
	s_nop 0
	v_fma_f32 v104, v58, v66, -v99
	v_fma_f32 v105, v59, v67, -v98
	v_fma_f32 v252, v58, v66, v99
	v_fma_f32 v99, v59, v66, v98
	v_mov_b32_e32 v98, v252
	v_mul_f32_e32 v58, v60, v62
	v_mul_f32_e32 v59, v61, v62
	s_nop 0
	v_fma_f32 v106, v60, v68, -v59
	v_fma_f32 v107, v61, v69, -v58
	v_fma_f32 v61, v61, v68, v58
	v_cvt_pk_bf16_f32 v59, v102, v65
	v_mad_i64_i32 v[64:65], s[0:1], v108, s47, v[122:123]
	v_cvt_pk_bf16_f32 v58, v100, v63
	v_cvt_pk_bf16_f32 v60, v104, v99
	v_cvt_pk_bf16_f32 v61, v106, v61
	v_lshl_add_u64 v[64:65], v[64:65], 0, v[124:125]
	global_store_dwordx4 v[64:65], v[58:61], off
	s_nop 1
	v_mul_f32_e32 v58, v54, v71
	v_mul_f32_e32 v59, v55, v71
	s_nop 0
	v_fma_f32 v60, v54, v70, -v59
	v_fma_f32 v61, v55, v71, -v58
	v_fma_f32 v55, v55, v70, v58
	v_mul_f32_e32 v58, v56, v0
	v_mul_f32_e32 v59, v57, v0
	s_nop 0
	v_fma_f32 v70, v56, v72, -v59
	v_fma_f32 v71, v57, v73, -v58
	v_fma_f32 v57, v57, v72, v58
	v_mul_f32_e32 v58, v46, v67
	v_mul_f32_e32 v59, v47, v67
	s_nop 0
	v_fma_f32 v72, v46, v66, -v59
	v_fma_f32 v73, v47, v67, -v58
	v_fma_f32 v59, v47, v66, v58
	v_mul_f32_e32 v46, v48, v62
	v_mul_f32_e32 v47, v49, v62
	s_nop 0
	v_fma_f32 v62, v48, v68, -v47
	v_fma_f32 v63, v49, v69, -v46
	v_fma_f32 v49, v49, v68, v46
	v_cvt_pk_bf16_f32 v46, v60, v55
	v_cvt_pk_bf16_f32 v47, v70, v57
	v_cvt_pk_bf16_f32 v48, v72, v59
	v_cvt_pk_bf16_f32 v49, v62, v49
	global_store_dwordx4 v[64:65], v[46:49], off offset:256
	s_nop 1
	v_mul_f32_e32 v46, v50, v79
	v_mul_f32_e32 v47, v51, v79
	v_mov_b32_e32 v0, v81
	v_fma_f32 v48, v50, v78, -v47
	v_fma_f32 v47, v51, v78, v46
	v_mul_f32_e32 v50, v52, v0
	v_mul_f32_e32 v51, v53, v0
	v_mov_b32_e32 v46, v77
	v_fma_f32 v54, v52, v80, -v51
	v_fma_f32 v55, v53, v81, -v50
	v_fma_f32 v51, v53, v80, v50
	v_mul_f32_e32 v52, v42, v75
	v_mul_f32_e32 v53, v43, v75
	s_nop 0
	v_fma_f32 v56, v42, v74, -v53
	v_fma_f32 v57, v43, v75, -v52
	v_fma_f32 v53, v43, v74, v52
	v_mul_f32_e32 v42, v44, v46
	v_mul_f32_e32 v43, v45, v46
	s_nop 0
	v_fma_f32 v58, v44, v76, -v43
	v_fma_f32 v59, v45, v77, -v42
	v_fma_f32 v45, v45, v76, v42
	v_cvt_pk_bf16_f32 v42, v48, v47
	v_mad_i64_i32 v[48:49], s[0:1], v109, s47, v[122:123]
	v_cvt_pk_bf16_f32 v43, v54, v51
	v_cvt_pk_bf16_f32 v44, v56, v53
	v_cvt_pk_bf16_f32 v45, v58, v45
	v_lshl_add_u64 v[48:49], v[48:49], 0, v[124:125]
	global_store_dwordx4 v[48:49], v[42:45], off
	s_nop 1
	v_mul_f32_e32 v42, v38, v79
	v_mul_f32_e32 v43, v39, v79
	s_nop 0
	v_fma_f32 v44, v38, v78, -v43
	v_fma_f32 v45, v39, v79, -v42
	v_fma_f32 v39, v39, v78, v42
	v_mul_f32_e32 v42, v40, v0
	v_mul_f32_e32 v43, v41, v0
	s_nop 0
	v_fma_f32 v50, v40, v80, -v43
	v_fma_f32 v51, v41, v81, -v42
	v_fma_f32 v41, v41, v80, v42
	v_mul_f32_e32 v42, v30, v75
	v_mul_f32_e32 v43, v31, v75
	s_nop 0
	v_fma_f32 v52, v30, v74, -v43
	v_fma_f32 v53, v31, v75, -v42
	v_fma_f32 v43, v31, v74, v42
	v_mul_f32_e32 v30, v32, v46
	v_mul_f32_e32 v31, v33, v46
	s_nop 0
	v_fma_f32 v46, v32, v76, -v31
	v_fma_f32 v47, v33, v77, -v30
	v_fma_f32 v33, v33, v76, v30
	v_cvt_pk_bf16_f32 v30, v44, v39
	v_cvt_pk_bf16_f32 v31, v50, v41
	v_cvt_pk_bf16_f32 v32, v52, v43
	v_cvt_pk_bf16_f32 v33, v46, v33
	global_store_dwordx4 v[48:49], v[30:33], off offset:256
	s_nop 1
	v_mul_f32_e32 v30, v34, v87
	v_mul_f32_e32 v31, v35, v87
	v_mov_b32_e32 v0, v89
	v_fma_f32 v32, v34, v86, -v31
	v_fma_f32 v31, v35, v86, v30
	v_mul_f32_e32 v34, v36, v0
	v_mul_f32_e32 v35, v37, v0
	v_mov_b32_e32 v30, v85
	v_fma_f32 v38, v36, v88, -v35
	v_fma_f32 v39, v37, v89, -v34
	v_fma_f32 v35, v37, v88, v34
	v_mul_f32_e32 v36, v26, v83
	v_mul_f32_e32 v37, v27, v83
	s_nop 0
	v_fma_f32 v40, v26, v82, -v37
	v_fma_f32 v41, v27, v83, -v36
	v_fma_f32 v37, v27, v82, v36
	v_mul_f32_e32 v26, v28, v30
	v_mul_f32_e32 v27, v29, v30
	s_nop 0
	v_fma_f32 v42, v28, v84, -v27
	v_fma_f32 v43, v29, v85, -v26
	v_fma_f32 v29, v29, v84, v26
	v_cvt_pk_bf16_f32 v26, v32, v31
	v_mad_i64_i32 v[32:33], s[0:1], v110, s47, v[122:123]
	v_cvt_pk_bf16_f32 v27, v38, v35
	v_cvt_pk_bf16_f32 v28, v40, v37
	v_cvt_pk_bf16_f32 v29, v42, v29
	v_lshl_add_u64 v[32:33], v[32:33], 0, v[124:125]
	global_store_dwordx4 v[32:33], v[26:29], off
	s_nop 1
	v_mul_f32_e32 v26, v22, v87
	v_mul_f32_e32 v27, v23, v87
	s_nop 0
	v_fma_f32 v28, v22, v86, -v27
	v_fma_f32 v29, v23, v87, -v26
	v_fma_f32 v23, v23, v86, v26
	v_mul_f32_e32 v26, v24, v0
	v_mul_f32_e32 v27, v25, v0
	s_nop 0
	v_fma_f32 v34, v24, v88, -v27
	v_fma_f32 v35, v25, v89, -v26
	v_fma_f32 v25, v25, v88, v26
	v_mul_f32_e32 v26, v14, v83
	v_mul_f32_e32 v27, v15, v83
	s_nop 0
	v_fma_f32 v36, v14, v82, -v27
	v_fma_f32 v37, v15, v83, -v26
	v_fma_f32 v27, v15, v82, v26
	v_mul_f32_e32 v14, v16, v30
	v_mul_f32_e32 v15, v17, v30
	s_nop 0
	v_fma_f32 v30, v16, v84, -v15
	v_fma_f32 v31, v17, v85, -v14
	v_fma_f32 v17, v17, v84, v14
	v_cvt_pk_bf16_f32 v14, v28, v23
	v_cvt_pk_bf16_f32 v15, v34, v25
	v_cvt_pk_bf16_f32 v16, v36, v27
	v_cvt_pk_bf16_f32 v17, v30, v17
	global_store_dwordx4 v[32:33], v[14:17], off offset:256
	s_nop 1
	v_mul_f32_e32 v14, v18, v95
	v_mul_f32_e32 v15, v19, v95
	v_mov_b32_e32 v0, v97
	v_fma_f32 v16, v18, v94, -v15
	v_fma_f32 v15, v19, v94, v14
	v_mul_f32_e32 v18, v20, v0
	v_mul_f32_e32 v19, v21, v0
	v_mov_b32_e32 v14, v93
	v_fma_f32 v22, v20, v96, -v19
	v_fma_f32 v23, v21, v97, -v18
	v_fma_f32 v19, v21, v96, v18
	v_mul_f32_e32 v20, v10, v91
	v_mul_f32_e32 v21, v11, v91
	s_nop 0
	v_fma_f32 v24, v10, v90, -v21
	v_fma_f32 v25, v11, v91, -v20
	v_fma_f32 v21, v11, v90, v20
	v_mul_f32_e32 v10, v12, v14
	v_mul_f32_e32 v11, v13, v14
	s_nop 0
	v_fma_f32 v26, v12, v92, -v11
	v_fma_f32 v27, v13, v93, -v10
	v_fma_f32 v13, v13, v92, v10
	v_cvt_pk_bf16_f32 v10, v16, v15
	v_mad_i64_i32 v[16:17], s[0:1], v111, s47, v[122:123]
	v_cvt_pk_bf16_f32 v11, v22, v19
	v_cvt_pk_bf16_f32 v12, v24, v21
	v_cvt_pk_bf16_f32 v13, v26, v13
	v_lshl_add_u64 v[16:17], v[16:17], 0, v[124:125]
	global_store_dwordx4 v[16:17], v[10:13], off
	s_nop 1
	v_mul_f32_e32 v10, v6, v95
	v_mul_f32_e32 v11, v7, v95
	s_nop 0
	v_fma_f32 v12, v6, v94, -v11
	v_fma_f32 v13, v7, v95, -v10
	v_fma_f32 v6, v6, v94, v11
	v_fma_f32 v7, v7, v94, v10
	v_mul_f32_e32 v10, v8, v0
	v_mul_f32_e32 v11, v9, v0
	s_nop 0
	v_fma_f32 v18, v8, v96, -v11
	v_fma_f32 v19, v9, v97, -v10
	v_fma_f32 v8, v8, v96, v11
	v_fma_f32 v9, v9, v96, v10
	v_mul_f32_e32 v10, v2, v91
	v_mul_f32_e32 v11, v3, v91
	s_nop 0
	v_fma_f32 v20, v2, v90, -v11
	v_fma_f32 v21, v3, v91, -v10
	v_fma_f32 v252, v2, v90, v11
	v_fma_f32 v11, v3, v90, v10
	v_mov_b32_e32 v10, v252
	v_mul_f32_e32 v2, v4, v14
	v_mul_f32_e32 v3, v5, v14
	s_nop 0
	v_fma_f32 v14, v4, v92, -v3
	v_fma_f32 v15, v5, v93, -v2
	v_fma_f32 v5, v5, v92, v2
	v_cvt_pk_bf16_f32 v2, v12, v7
	v_cvt_pk_bf16_f32 v3, v18, v9
	v_cvt_pk_bf16_f32 v4, v20, v11
	v_cvt_pk_bf16_f32 v5, v14, v5
	global_store_dwordx4 v[16:17], v[2:5], off offset:256
	s_branch .LBB0_128
